# first grid barrier: census loads issued together (one wait) instead of 13 serialised round trips
# baseline (speedup 1.0000x reference)
.LBB0_133:
	global_load_dword v2, v16, s[96:97] sc1
	s_waitcnt lgkmcnt(0)
	global_load_dword v0, v16, s[50:51] sc1
	global_load_dword v1, v16, s[52:53] sc1
	v_readlane_b32 s6, v249, 7
	v_readlane_b32 s7, v249, 8
	s_nop 4
	global_load_dword v3, v16, s[6:7] sc1
	v_readlane_b32 s6, v249, 9
	v_readlane_b32 s7, v249, 10
	s_nop 4
	global_load_dword v4, v16, s[6:7] sc1
	v_readlane_b32 s6, v249, 11
	v_readlane_b32 s7, v249, 12
	s_nop 4
	global_load_dword v5, v16, s[6:7] sc1
	v_readlane_b32 s6, v249, 13
	v_readlane_b32 s7, v249, 14
	s_nop 4
	global_load_dword v6, v16, s[6:7] sc1
	v_readlane_b32 s6, v249, 15
	v_readlane_b32 s7, v249, 16
	s_nop 4
	global_load_dword v7, v16, s[6:7] sc1
	v_readlane_b32 s6, v249, 17
	v_readlane_b32 s7, v249, 18
	s_nop 4
	global_load_dword v8, v16, s[6:7] sc1
	v_readlane_b32 s6, v249, 19
	v_readlane_b32 s7, v249, 20
	s_nop 4
	global_load_dword v9, v16, s[6:7] sc1
	v_readlane_b32 s6, v249, 21
	v_readlane_b32 s7, v249, 22
	s_nop 4
	global_load_dword v10, v16, s[6:7] sc1
	v_readlane_b32 s6, v249, 23
	v_readlane_b32 s7, v249, 24
	s_nop 4
	global_load_dword v11, v16, s[6:7] sc1
	v_readlane_b32 s6, v249, 25
	v_readlane_b32 s7, v249, 26
	s_nop 4
	global_load_dword v12, v16, s[6:7] sc1
	v_readlane_b32 s6, v249, 27
	v_readlane_b32 s7, v249, 28
	s_nop 4
	global_load_dword v13, v16, s[6:7] sc1
	v_readlane_b32 s6, v249, 29
	v_readlane_b32 s7, v249, 30
	s_nop 4
	global_load_dword v14, v16, s[6:7] sc1
	v_readlane_b32 s6, v249, 31
	v_readlane_b32 s7, v249, 32
	s_nop 4
	global_load_dword v15, v16, s[6:7] sc1
	s_mov_b64 s[24:25], -1
	s_mov_b64 s[26:27], -1
	s_waitcnt vmcnt(0)
	v_add_u32_e32 v17, v0, v2
	v_add_u32_e32 v17, v17, v1
	v_add_u32_e32 v17, v17, v3
	v_add_u32_e32 v17, v17, v4
	v_add_u32_e32 v17, v17, v5
	v_add_u32_e32 v17, v17, v6
	v_add_u32_e32 v17, v17, v7
	v_add_u32_e32 v17, v17, v8
	v_add_u32_e32 v17, v17, v9
	v_add_u32_e32 v17, v17, v10
	v_add_u32_e32 v17, v17, v11
	v_add_u32_e32 v17, v17, v12
	v_add_u32_e32 v17, v17, v13
	v_add_u32_e32 v17, v17, v14
	v_add_u32_e32 v17, v17, v15
	v_cmp_eq_u32_e32 vcc, s72, v17
	s_cbranch_vccnz .LBB0_132
	s_and_b32 s5, s4, 0xff
	s_cmp_eq_u32 s5, 0
	s_mov_b64 s[28:29], -1
	s_sleep 1
	s_cbranch_scc1 .LBB0_137
	s_and_b64 vcc, exec, s[28:29]
	s_cbranch_vccz .LBB0_132
